# gated-merge mid-K hook: gate loads pipelined four steps ahead (32-bit offsets from the gate base in SGPRs free the registers for the deeper ring)
# speedup vs baseline: 1.0037x; 1.0002x over previous
.LBB0_263:
	v_mov_b32_e32 v130, v1
	v_mov_b32_e32 v131, v154
	s_and_b32 s22, s20, 0xc00
	v_add_u32_e32 v157, s64, v130
	v_lshl_add_u32 v166, v131, 3, s65
	v_add_u32_e32 v131, s93, v157
	v_mov_b64_e32 v[132:133], s[10:11]
	s_add_i32 s40, s22, 0xfffffc00
	v_add_u32_e32 v130, s92, v166
	v_mad_i64_i32 v[134:135], s[22:23], v131, s24, v[132:133]
	s_lshl_b64 s[22:23], s[40:41], 1
	v_ashrrev_i32_e32 v131, 31, v130
	v_lshl_add_u64 v[136:137], v[134:135], 0, s[22:23]
	v_lshlrev_b64 v[134:135], 1, v[130:131]
	v_lshl_add_u64 v[130:131], v[136:137], 0, v[134:135]
	v_subrev_u32_e32 v173, s10, v130
	v_add_u32_e32 v130, s94, v166
	v_ashrrev_i32_e32 v131, 31, v130
	v_lshlrev_b64 v[130:131], 1, v[130:131]
	v_lshl_add_u64 v[136:137], v[136:137], 0, v[130:131]
	v_subrev_u32_e32 v222, s10, v136
	v_add_u32_e32 v136, s95, v157
	v_mad_i64_i32 v[136:137], s[26:27], v136, s24, v[132:133]
	v_lshl_add_u64 v[136:137], v[136:137], 0, s[22:23]
	v_lshl_add_u64 v[162:163], v[136:137], 0, v[134:135]
	v_subrev_u32_e32 v223, s10, v162
	v_lshl_add_u64 v[136:137], v[136:137], 0, v[130:131]
	v_subrev_u32_e32 v224, s10, v136
	v_add_u32_e32 v136, s96, v157
	v_mad_i64_i32 v[136:137], s[26:27], v136, s24, v[132:133]
	v_lshl_add_u64 v[136:137], v[136:137], 0, s[22:23]
	v_lshl_add_u64 v[162:163], v[136:137], 0, v[134:135]
	v_subrev_u32_e32 v226, s10, v162
	v_lshl_add_u64 v[136:137], v[136:137], 0, v[130:131]
	v_subrev_u32_e32 v227, s10, v136
	v_add_u32_e32 v136, s97, v157
	v_mad_i64_i32 v[136:137], s[26:27], v136, s24, v[132:133]
	v_lshl_add_u64 v[136:137], v[136:137], 0, s[22:23]
	v_lshl_add_u64 v[162:163], v[136:137], 0, v[134:135]
	v_subrev_u32_e32 v228, s10, v162
	v_lshl_add_u64 v[136:137], v[136:137], 0, v[130:131]
	v_subrev_u32_e32 v232, s10, v136
	v_add_u32_e32 v136, s37, v157
	v_mad_i64_i32 v[136:137], s[26:27], v136, s24, v[132:133]
	v_lshl_add_u64 v[136:137], v[136:137], 0, s[22:23]
	v_lshl_add_u64 v[162:163], v[136:137], 0, v[134:135]
	v_subrev_u32_e32 v233, s10, v162
	v_lshl_add_u64 v[136:137], v[136:137], 0, v[130:131]
	v_subrev_u32_e32 v240, s10, v136
	v_add_u32_e32 v136, s89, v157
	v_mad_i64_i32 v[136:137], s[26:27], v136, s24, v[132:133]
	v_lshl_add_u64 v[136:137], v[136:137], 0, s[22:23]
	v_lshl_add_u64 v[162:163], v[136:137], 0, v[134:135]
	v_subrev_u32_e32 v241, s10, v162
	v_lshl_add_u64 v[136:137], v[136:137], 0, v[130:131]
	v_subrev_u32_e32 v242, s10, v136
	v_add_u32_e32 v136, s1, v157
	v_mad_i64_i32 v[136:137], s[26:27], v136, s24, v[132:133]
	v_lshl_add_u64 v[136:137], v[136:137], 0, s[22:23]
	v_lshl_add_u64 v[162:163], v[136:137], 0, v[134:135]
	v_subrev_u32_e32 v243, s10, v162
	v_lshl_add_u64 v[136:137], v[136:137], 0, v[130:131]
	v_subrev_u32_e32 v244, s10, v136
	v_add_u32_e32 v136, s0, v157
	v_mad_i64_i32 v[132:133], s[26:27], v136, s24, v[132:133]
	v_lshl_add_u64 v[132:133], v[132:133], 0, s[22:23]
	v_lshl_add_u64 v[158:159], v[132:133], 0, v[134:135]
	v_subrev_u32_e32 v245, s10, v158
	v_lshl_add_u64 v[134:135], v[132:133], 0, v[130:131]
	v_subrev_u32_e32 v246, s10, v134
	global_load_dwordx4 v[174:177], v173, s[10:11]
	global_load_dwordx4 v[178:181], v173, s[10:11] offset:2048
	global_load_dwordx4 v[182:185], v222, s[10:11]
	global_load_dwordx4 v[186:189], v222, s[10:11] offset:2048
	global_load_dwordx4 v[190:193], v223, s[10:11]
	global_load_dwordx4 v[194:197], v223, s[10:11] offset:2048
	global_load_dwordx4 v[198:201], v224, s[10:11]
	global_load_dwordx4 v[202:205], v224, s[10:11] offset:2048
	global_load_dwordx4 v[206:209], v226, s[10:11]
	global_load_dwordx4 v[210:213], v226, s[10:11] offset:2048
	s_waitcnt vmcnt(8)
	v_lshlrev_b32_e32 v130, 16, v178
	v_and_b32_e32 v131, 0xffff0000, v178
	v_rcp_f32_e32 v130, v130
	v_rcp_f32_e32 v131, v131
	v_lshlrev_b32_e32 v167, 16, v179
	v_and_b32_e32 v168, 0xffff0000, v179
	v_lshlrev_b32_e32 v162, 16, v180
	v_and_b32_e32 v163, 0xffff0000, v180
	v_rcp_f32_e32 v162, v162
	v_rcp_f32_e32 v163, v163
	v_lshlrev_b32_e32 v169, 16, v181
	v_and_b32_e32 v170, 0xffff0000, v181
	v_lshlrev_b32_e32 v164, 16, v174
	v_and_b32_e32 v165, 0xffff0000, v174
	v_pk_mul_f32 v[130:131], v[130:131], v[164:165]
	v_rcp_f32_e32 v158, v169
	v_pk_mul_f32 v[126:127], v[126:127], v[130:131]
	v_lshlrev_b32_e32 v130, 16, v176
	v_and_b32_e32 v131, 0xffff0000, v176
	v_pk_mul_f32 v[130:131], v[162:163], v[130:131]
	v_lshlrev_b32_e32 v162, 16, v175
	v_pk_mul_f32 v[122:123], v[122:123], v[130:131]
	v_rcp_f32_e32 v130, v167
	v_rcp_f32_e32 v131, v168
	v_and_b32_e32 v163, 0xffff0000, v175
	v_rcp_f32_e32 v159, v170
	v_pk_mul_f32 v[130:131], v[130:131], v[162:163]
	s_nop 0
	v_pk_mul_f32 v[128:129], v[128:129], v[130:131]
	v_lshlrev_b32_e32 v130, 16, v177
	v_and_b32_e32 v131, 0xffff0000, v177
	v_pk_mul_f32 v[130:131], v[158:159], v[130:131]
	s_nop 0
	v_pk_mul_f32 v[124:125], v[124:125], v[130:131]
	global_load_dwordx4 v[214:217], v227, s[10:11]
	global_load_dwordx4 v[218:221], v227, s[10:11] offset:2048
	s_waitcnt vmcnt(8)
	v_lshlrev_b32_e32 v136, 16, v186
	v_and_b32_e32 v137, 0xffff0000, v186
	v_rcp_f32_e32 v136, v136
	v_rcp_f32_e32 v137, v137
	v_lshlrev_b32_e32 v166, 16, v187
	v_and_b32_e32 v167, 0xffff0000, v187
	v_lshlrev_b32_e32 v162, 16, v188
	v_and_b32_e32 v163, 0xffff0000, v188
	v_rcp_f32_e32 v162, v162
	v_rcp_f32_e32 v163, v163
	v_lshlrev_b32_e32 v168, 16, v189
	v_and_b32_e32 v169, 0xffff0000, v189
	v_lshlrev_b32_e32 v164, 16, v182
	v_and_b32_e32 v165, 0xffff0000, v182
	v_pk_mul_f32 v[136:137], v[136:137], v[164:165]
	v_rcp_f32_e32 v158, v168
	v_pk_mul_f32 v[118:119], v[118:119], v[136:137]
	v_lshlrev_b32_e32 v136, 16, v184
	v_and_b32_e32 v137, 0xffff0000, v184
	v_pk_mul_f32 v[136:137], v[162:163], v[136:137]
	v_lshlrev_b32_e32 v162, 16, v183
	v_pk_mul_f32 v[114:115], v[114:115], v[136:137]
	v_rcp_f32_e32 v136, v166
	v_rcp_f32_e32 v137, v167
	v_and_b32_e32 v163, 0xffff0000, v183
	v_rcp_f32_e32 v159, v169
	v_pk_mul_f32 v[136:137], v[136:137], v[162:163]
	s_nop 0
	v_pk_mul_f32 v[120:121], v[120:121], v[136:137]
	v_lshlrev_b32_e32 v136, 16, v185
	v_and_b32_e32 v137, 0xffff0000, v185
	v_pk_mul_f32 v[136:137], v[158:159], v[136:137]
	s_nop 0
	v_pk_mul_f32 v[116:117], v[116:117], v[136:137]
	global_load_dwordx4 v[174:177], v228, s[10:11]
	global_load_dwordx4 v[178:181], v228, s[10:11] offset:2048
	s_waitcnt vmcnt(8)
	s_nop 0
	v_lshlrev_b32_e32 v166, 16, v194
	v_and_b32_e32 v167, 0xffff0000, v194
	v_lshlrev_b32_e32 v168, 16, v195
	v_and_b32_e32 v169, 0xffff0000, v195
	v_lshlrev_b32_e32 v163, 16, v196
	v_and_b32_e32 v170, 0xffff0000, v196
	v_rcp_f32_e32 v162, v166
	v_rcp_f32_e32 v164, v163
	v_rcp_f32_e32 v163, v167
	v_lshlrev_b32_e32 v171, 16, v197
	v_and_b32_e32 v172, 0xffff0000, v197
	v_rcp_f32_e32 v165, v170
	v_lshlrev_b32_e32 v166, 16, v190
	v_and_b32_e32 v167, 0xffff0000, v190
	v_pk_mul_f32 v[162:163], v[162:163], v[166:167]
	v_rcp_f32_e32 v158, v171
	v_pk_mul_f32 v[110:111], v[110:111], v[162:163]
	v_lshlrev_b32_e32 v162, 16, v192
	v_and_b32_e32 v163, 0xffff0000, v192
	v_pk_mul_f32 v[162:163], v[164:165], v[162:163]
	v_lshlrev_b32_e32 v164, 16, v191
	v_pk_mul_f32 v[106:107], v[106:107], v[162:163]
	v_rcp_f32_e32 v162, v168
	v_rcp_f32_e32 v163, v169
	v_and_b32_e32 v165, 0xffff0000, v191
	v_rcp_f32_e32 v159, v172
	v_lshlrev_b32_e32 v160, 16, v193
	v_and_b32_e32 v161, 0xffff0000, v193
	v_pk_mul_f32 v[162:163], v[162:163], v[164:165]
	v_pk_mul_f32 v[158:159], v[158:159], v[160:161]
	v_pk_mul_f32 v[112:113], v[112:113], v[162:163]
	v_pk_mul_f32 v[108:109], v[108:109], v[158:159]
	global_load_dwordx4 v[182:185], v232, s[10:11]
	global_load_dwordx4 v[186:189], v232, s[10:11] offset:2048
	s_waitcnt vmcnt(8)
	v_lshlrev_b32_e32 v136, 16, v202
	v_and_b32_e32 v137, 0xffff0000, v202
	v_rcp_f32_e32 v136, v136
	v_rcp_f32_e32 v137, v137
	v_lshlrev_b32_e32 v166, 16, v203
	v_and_b32_e32 v167, 0xffff0000, v203
	v_lshlrev_b32_e32 v162, 16, v204
	v_and_b32_e32 v163, 0xffff0000, v204
	v_rcp_f32_e32 v162, v162
	v_rcp_f32_e32 v163, v163
	v_lshlrev_b32_e32 v168, 16, v205
	v_and_b32_e32 v169, 0xffff0000, v205
	v_lshlrev_b32_e32 v164, 16, v198
	v_and_b32_e32 v165, 0xffff0000, v198
	v_pk_mul_f32 v[136:137], v[136:137], v[164:165]
	v_rcp_f32_e32 v158, v168
	v_pk_mul_f32 v[102:103], v[102:103], v[136:137]
	v_lshlrev_b32_e32 v136, 16, v200
	v_and_b32_e32 v137, 0xffff0000, v200
	v_pk_mul_f32 v[136:137], v[162:163], v[136:137]
	v_lshlrev_b32_e32 v162, 16, v199
	v_pk_mul_f32 v[98:99], v[98:99], v[136:137]
	v_rcp_f32_e32 v136, v166
	v_rcp_f32_e32 v137, v167
	v_and_b32_e32 v163, 0xffff0000, v199
	v_rcp_f32_e32 v159, v169
	v_pk_mul_f32 v[136:137], v[136:137], v[162:163]
	s_nop 0
	v_pk_mul_f32 v[104:105], v[104:105], v[136:137]
	v_lshlrev_b32_e32 v136, 16, v201
	v_and_b32_e32 v137, 0xffff0000, v201
	v_pk_mul_f32 v[136:137], v[158:159], v[136:137]
	s_nop 0
	v_pk_mul_f32 v[100:101], v[100:101], v[136:137]
	global_load_dwordx4 v[190:193], v233, s[10:11]
	global_load_dwordx4 v[194:197], v233, s[10:11] offset:2048
	s_waitcnt vmcnt(8)
	s_nop 0
	v_lshlrev_b32_e32 v166, 16, v210
	v_and_b32_e32 v167, 0xffff0000, v210
	v_lshlrev_b32_e32 v168, 16, v211
	v_and_b32_e32 v169, 0xffff0000, v211
	v_lshlrev_b32_e32 v163, 16, v212
	v_and_b32_e32 v170, 0xffff0000, v212
	v_rcp_f32_e32 v162, v166
	v_rcp_f32_e32 v164, v163
	v_rcp_f32_e32 v163, v167
	v_lshlrev_b32_e32 v171, 16, v213
	v_and_b32_e32 v172, 0xffff0000, v213
	v_rcp_f32_e32 v165, v170
	v_lshlrev_b32_e32 v166, 16, v206
	v_and_b32_e32 v167, 0xffff0000, v206
	v_pk_mul_f32 v[162:163], v[162:163], v[166:167]
	v_rcp_f32_e32 v158, v171
	v_pk_mul_f32 v[94:95], v[94:95], v[162:163]
	v_lshlrev_b32_e32 v162, 16, v208
	v_and_b32_e32 v163, 0xffff0000, v208
	v_pk_mul_f32 v[162:163], v[164:165], v[162:163]
	v_lshlrev_b32_e32 v164, 16, v207
	v_pk_mul_f32 v[90:91], v[90:91], v[162:163]
	v_rcp_f32_e32 v162, v168
	v_rcp_f32_e32 v163, v169
	v_and_b32_e32 v165, 0xffff0000, v207
	v_rcp_f32_e32 v159, v172
	v_lshlrev_b32_e32 v160, 16, v209
	v_and_b32_e32 v161, 0xffff0000, v209
	v_pk_mul_f32 v[162:163], v[162:163], v[164:165]
	v_pk_mul_f32 v[158:159], v[158:159], v[160:161]
	v_pk_mul_f32 v[96:97], v[96:97], v[162:163]
	v_pk_mul_f32 v[92:93], v[92:93], v[158:159]
	global_load_dwordx4 v[198:201], v240, s[10:11]
	global_load_dwordx4 v[202:205], v240, s[10:11] offset:2048
	s_waitcnt vmcnt(8)
	v_lshlrev_b32_e32 v136, 16, v218
	v_and_b32_e32 v137, 0xffff0000, v218
	v_rcp_f32_e32 v136, v136
	v_rcp_f32_e32 v137, v137
	v_lshlrev_b32_e32 v166, 16, v219
	v_and_b32_e32 v167, 0xffff0000, v219
	v_lshlrev_b32_e32 v162, 16, v220
	v_and_b32_e32 v163, 0xffff0000, v220
	v_rcp_f32_e32 v162, v162
	v_rcp_f32_e32 v163, v163
	v_lshlrev_b32_e32 v168, 16, v221
	v_and_b32_e32 v169, 0xffff0000, v221
	v_lshlrev_b32_e32 v164, 16, v214
	v_and_b32_e32 v165, 0xffff0000, v214
	v_pk_mul_f32 v[136:137], v[136:137], v[164:165]
	v_rcp_f32_e32 v158, v168
	v_pk_mul_f32 v[86:87], v[86:87], v[136:137]
	v_lshlrev_b32_e32 v136, 16, v216
	v_and_b32_e32 v137, 0xffff0000, v216
	v_pk_mul_f32 v[136:137], v[162:163], v[136:137]
	v_lshlrev_b32_e32 v162, 16, v215
	v_pk_mul_f32 v[82:83], v[82:83], v[136:137]
	v_rcp_f32_e32 v136, v166
	v_rcp_f32_e32 v137, v167
	v_and_b32_e32 v163, 0xffff0000, v215
	v_rcp_f32_e32 v159, v169
	v_pk_mul_f32 v[136:137], v[136:137], v[162:163]
	s_nop 0
	v_pk_mul_f32 v[88:89], v[88:89], v[136:137]
	v_lshlrev_b32_e32 v136, 16, v217
	v_and_b32_e32 v137, 0xffff0000, v217
	v_pk_mul_f32 v[136:137], v[158:159], v[136:137]
	s_nop 0
	v_pk_mul_f32 v[84:85], v[84:85], v[136:137]
	global_load_dwordx4 v[206:209], v241, s[10:11]
	global_load_dwordx4 v[210:213], v241, s[10:11] offset:2048
	s_waitcnt vmcnt(8)
	s_nop 0
	v_lshlrev_b32_e32 v166, 16, v178
	v_and_b32_e32 v167, 0xffff0000, v178
	v_lshlrev_b32_e32 v168, 16, v179
	v_and_b32_e32 v169, 0xffff0000, v179
	v_lshlrev_b32_e32 v163, 16, v180
	v_and_b32_e32 v170, 0xffff0000, v180
	v_rcp_f32_e32 v162, v166
	v_rcp_f32_e32 v164, v163
	v_rcp_f32_e32 v163, v167
	v_lshlrev_b32_e32 v171, 16, v181
	v_and_b32_e32 v172, 0xffff0000, v181
	v_rcp_f32_e32 v165, v170
	v_lshlrev_b32_e32 v166, 16, v174
	v_and_b32_e32 v167, 0xffff0000, v174
	v_pk_mul_f32 v[162:163], v[162:163], v[166:167]
	v_rcp_f32_e32 v158, v171
	v_pk_mul_f32 v[78:79], v[78:79], v[162:163]
	v_lshlrev_b32_e32 v162, 16, v176
	v_and_b32_e32 v163, 0xffff0000, v176
	v_pk_mul_f32 v[162:163], v[164:165], v[162:163]
	v_lshlrev_b32_e32 v164, 16, v175
	v_pk_mul_f32 v[74:75], v[74:75], v[162:163]
	v_rcp_f32_e32 v162, v168
	v_rcp_f32_e32 v163, v169
	v_and_b32_e32 v165, 0xffff0000, v175
	v_rcp_f32_e32 v159, v172
	v_lshlrev_b32_e32 v160, 16, v177
	v_and_b32_e32 v161, 0xffff0000, v177
	v_pk_mul_f32 v[162:163], v[162:163], v[164:165]
	v_pk_mul_f32 v[158:159], v[158:159], v[160:161]
	v_pk_mul_f32 v[80:81], v[80:81], v[162:163]
	v_pk_mul_f32 v[76:77], v[76:77], v[158:159]
	global_load_dwordx4 v[214:217], v242, s[10:11]
	global_load_dwordx4 v[218:221], v242, s[10:11] offset:2048
	s_waitcnt vmcnt(8)
	v_lshlrev_b32_e32 v136, 16, v186
	v_and_b32_e32 v137, 0xffff0000, v186
	v_rcp_f32_e32 v136, v136
	v_rcp_f32_e32 v137, v137
	v_lshlrev_b32_e32 v166, 16, v187
	v_and_b32_e32 v167, 0xffff0000, v187
	v_lshlrev_b32_e32 v162, 16, v188
	v_and_b32_e32 v163, 0xffff0000, v188
	v_rcp_f32_e32 v162, v162
	v_rcp_f32_e32 v163, v163
	v_lshlrev_b32_e32 v168, 16, v189
	v_and_b32_e32 v169, 0xffff0000, v189
	v_lshlrev_b32_e32 v164, 16, v182
	v_and_b32_e32 v165, 0xffff0000, v182
	v_pk_mul_f32 v[136:137], v[136:137], v[164:165]
	v_rcp_f32_e32 v158, v168
	v_pk_mul_f32 v[70:71], v[70:71], v[136:137]
	v_lshlrev_b32_e32 v136, 16, v184
	v_and_b32_e32 v137, 0xffff0000, v184
	v_pk_mul_f32 v[136:137], v[162:163], v[136:137]
	v_lshlrev_b32_e32 v162, 16, v183
	v_pk_mul_f32 v[66:67], v[66:67], v[136:137]
	v_rcp_f32_e32 v136, v166
	v_rcp_f32_e32 v137, v167
	v_and_b32_e32 v163, 0xffff0000, v183
	v_rcp_f32_e32 v159, v169
	v_pk_mul_f32 v[136:137], v[136:137], v[162:163]
	s_nop 0
	v_pk_mul_f32 v[72:73], v[72:73], v[136:137]
	v_lshlrev_b32_e32 v136, 16, v185
	v_and_b32_e32 v137, 0xffff0000, v185
	v_pk_mul_f32 v[136:137], v[158:159], v[136:137]
	s_nop 0
	v_pk_mul_f32 v[68:69], v[68:69], v[136:137]
	global_load_dwordx4 v[174:177], v243, s[10:11]
	global_load_dwordx4 v[178:181], v243, s[10:11] offset:2048
	s_waitcnt vmcnt(8)
	s_nop 0
	v_lshlrev_b32_e32 v166, 16, v194
	v_and_b32_e32 v167, 0xffff0000, v194
	v_lshlrev_b32_e32 v168, 16, v195
	v_and_b32_e32 v169, 0xffff0000, v195
	v_lshlrev_b32_e32 v163, 16, v196
	v_and_b32_e32 v170, 0xffff0000, v196
	v_rcp_f32_e32 v162, v166
	v_rcp_f32_e32 v164, v163
	v_rcp_f32_e32 v163, v167
	v_lshlrev_b32_e32 v171, 16, v197
	v_and_b32_e32 v172, 0xffff0000, v197
	v_rcp_f32_e32 v165, v170
	v_lshlrev_b32_e32 v166, 16, v190
	v_and_b32_e32 v167, 0xffff0000, v190
	v_pk_mul_f32 v[162:163], v[162:163], v[166:167]
	v_rcp_f32_e32 v158, v171
	v_pk_mul_f32 v[62:63], v[62:63], v[162:163]
	v_lshlrev_b32_e32 v162, 16, v192
	v_and_b32_e32 v163, 0xffff0000, v192
	v_pk_mul_f32 v[162:163], v[164:165], v[162:163]
	v_lshlrev_b32_e32 v164, 16, v191
	v_pk_mul_f32 v[58:59], v[58:59], v[162:163]
	v_rcp_f32_e32 v162, v168
	v_rcp_f32_e32 v163, v169
	v_and_b32_e32 v165, 0xffff0000, v191
	v_rcp_f32_e32 v159, v172
	v_lshlrev_b32_e32 v160, 16, v193
	v_and_b32_e32 v161, 0xffff0000, v193
	v_pk_mul_f32 v[162:163], v[162:163], v[164:165]
	v_pk_mul_f32 v[158:159], v[158:159], v[160:161]
	v_pk_mul_f32 v[64:65], v[64:65], v[162:163]
	v_pk_mul_f32 v[60:61], v[60:61], v[158:159]
	global_load_dwordx4 v[182:185], v244, s[10:11]
	global_load_dwordx4 v[186:189], v244, s[10:11] offset:2048
	s_waitcnt vmcnt(8)
	v_lshlrev_b32_e32 v136, 16, v202
	v_and_b32_e32 v137, 0xffff0000, v202
	v_rcp_f32_e32 v136, v136
	v_rcp_f32_e32 v137, v137
	v_lshlrev_b32_e32 v166, 16, v203
	v_and_b32_e32 v167, 0xffff0000, v203
	v_lshlrev_b32_e32 v162, 16, v204
	v_and_b32_e32 v163, 0xffff0000, v204
	v_rcp_f32_e32 v162, v162
	v_rcp_f32_e32 v163, v163
	v_lshlrev_b32_e32 v168, 16, v205
	v_and_b32_e32 v169, 0xffff0000, v205
	v_lshlrev_b32_e32 v164, 16, v198
	v_and_b32_e32 v165, 0xffff0000, v198
	v_pk_mul_f32 v[136:137], v[136:137], v[164:165]
	v_rcp_f32_e32 v158, v168
	v_pk_mul_f32 v[54:55], v[54:55], v[136:137]
	v_lshlrev_b32_e32 v136, 16, v200
	v_and_b32_e32 v137, 0xffff0000, v200
	v_pk_mul_f32 v[136:137], v[162:163], v[136:137]
	v_lshlrev_b32_e32 v162, 16, v199
	v_pk_mul_f32 v[50:51], v[50:51], v[136:137]
	v_rcp_f32_e32 v136, v166
	v_rcp_f32_e32 v137, v167
	v_and_b32_e32 v163, 0xffff0000, v199
	v_rcp_f32_e32 v159, v169
	v_pk_mul_f32 v[136:137], v[136:137], v[162:163]
	s_nop 0
	v_pk_mul_f32 v[56:57], v[56:57], v[136:137]
	v_lshlrev_b32_e32 v136, 16, v201
	v_and_b32_e32 v137, 0xffff0000, v201
	v_pk_mul_f32 v[136:137], v[158:159], v[136:137]
	s_nop 0
	v_pk_mul_f32 v[52:53], v[52:53], v[136:137]
	global_load_dwordx4 v[190:193], v245, s[10:11]
	global_load_dwordx4 v[194:197], v245, s[10:11] offset:2048
	s_waitcnt vmcnt(8)
	s_nop 0
	v_lshlrev_b32_e32 v166, 16, v210
	v_and_b32_e32 v167, 0xffff0000, v210
	v_lshlrev_b32_e32 v168, 16, v211
	v_and_b32_e32 v169, 0xffff0000, v211
	v_lshlrev_b32_e32 v163, 16, v212
	v_and_b32_e32 v170, 0xffff0000, v212
	v_rcp_f32_e32 v162, v166
	v_rcp_f32_e32 v164, v163
	v_rcp_f32_e32 v163, v167
	v_lshlrev_b32_e32 v171, 16, v213
	v_and_b32_e32 v172, 0xffff0000, v213
	v_rcp_f32_e32 v165, v170
	v_lshlrev_b32_e32 v166, 16, v206
	v_and_b32_e32 v167, 0xffff0000, v206
	v_pk_mul_f32 v[162:163], v[162:163], v[166:167]
	v_rcp_f32_e32 v158, v171
	v_pk_mul_f32 v[46:47], v[46:47], v[162:163]
	v_lshlrev_b32_e32 v162, 16, v208
	v_and_b32_e32 v163, 0xffff0000, v208
	v_pk_mul_f32 v[162:163], v[164:165], v[162:163]
	v_lshlrev_b32_e32 v164, 16, v207
	v_pk_mul_f32 v[42:43], v[42:43], v[162:163]
	v_rcp_f32_e32 v162, v168
	v_rcp_f32_e32 v163, v169
	v_and_b32_e32 v165, 0xffff0000, v207
	v_rcp_f32_e32 v159, v172
	v_lshlrev_b32_e32 v160, 16, v209
	v_and_b32_e32 v161, 0xffff0000, v209
	v_pk_mul_f32 v[162:163], v[162:163], v[164:165]
	v_pk_mul_f32 v[158:159], v[158:159], v[160:161]
	v_pk_mul_f32 v[48:49], v[48:49], v[162:163]
	v_pk_mul_f32 v[44:45], v[44:45], v[158:159]
	global_load_dwordx4 v[198:201], v246, s[10:11]
	global_load_dwordx4 v[202:205], v246, s[10:11] offset:2048
	s_waitcnt vmcnt(8)
	v_lshlrev_b32_e32 v136, 16, v218
	v_and_b32_e32 v137, 0xffff0000, v218
	v_rcp_f32_e32 v136, v136
	v_rcp_f32_e32 v137, v137
	v_lshlrev_b32_e32 v166, 16, v219
	v_and_b32_e32 v167, 0xffff0000, v219
	v_lshlrev_b32_e32 v162, 16, v220
	v_and_b32_e32 v163, 0xffff0000, v220
	v_rcp_f32_e32 v162, v162
	v_rcp_f32_e32 v163, v163
	v_lshlrev_b32_e32 v168, 16, v221
	v_and_b32_e32 v169, 0xffff0000, v221
	v_lshlrev_b32_e32 v164, 16, v214
	v_and_b32_e32 v165, 0xffff0000, v214
	v_pk_mul_f32 v[136:137], v[136:137], v[164:165]
	v_rcp_f32_e32 v158, v168
	v_pk_mul_f32 v[38:39], v[38:39], v[136:137]
	v_lshlrev_b32_e32 v136, 16, v216
	v_and_b32_e32 v137, 0xffff0000, v216
	v_pk_mul_f32 v[136:137], v[162:163], v[136:137]
	v_lshlrev_b32_e32 v162, 16, v215
	v_pk_mul_f32 v[34:35], v[34:35], v[136:137]
	v_rcp_f32_e32 v136, v166
	v_rcp_f32_e32 v137, v167
	v_and_b32_e32 v163, 0xffff0000, v215
	v_rcp_f32_e32 v159, v169
	v_pk_mul_f32 v[136:137], v[136:137], v[162:163]
	s_nop 0
	v_pk_mul_f32 v[40:41], v[40:41], v[136:137]
	v_lshlrev_b32_e32 v136, 16, v217
	v_and_b32_e32 v137, 0xffff0000, v217
	v_pk_mul_f32 v[136:137], v[158:159], v[136:137]
	s_nop 0
	v_pk_mul_f32 v[36:37], v[36:37], v[136:137]
	s_waitcnt vmcnt(6)
	s_nop 0
	v_lshlrev_b32_e32 v166, 16, v178
	v_and_b32_e32 v167, 0xffff0000, v178
	v_lshlrev_b32_e32 v168, 16, v179
	v_and_b32_e32 v169, 0xffff0000, v179
	v_lshlrev_b32_e32 v163, 16, v180
	v_and_b32_e32 v170, 0xffff0000, v180
	v_rcp_f32_e32 v162, v166
	v_rcp_f32_e32 v164, v163
	v_rcp_f32_e32 v163, v167
	v_lshlrev_b32_e32 v171, 16, v181
	v_and_b32_e32 v172, 0xffff0000, v181
	v_rcp_f32_e32 v165, v170
	v_lshlrev_b32_e32 v166, 16, v174
	v_and_b32_e32 v167, 0xffff0000, v174
	v_pk_mul_f32 v[162:163], v[162:163], v[166:167]
	v_rcp_f32_e32 v158, v171
	v_pk_mul_f32 v[30:31], v[30:31], v[162:163]
	v_lshlrev_b32_e32 v162, 16, v176
	v_and_b32_e32 v163, 0xffff0000, v176
	v_pk_mul_f32 v[162:163], v[164:165], v[162:163]
	v_lshlrev_b32_e32 v164, 16, v175
	v_pk_mul_f32 v[26:27], v[26:27], v[162:163]
	v_rcp_f32_e32 v162, v168
	v_rcp_f32_e32 v163, v169
	v_and_b32_e32 v165, 0xffff0000, v175
	v_rcp_f32_e32 v159, v172
	v_lshlrev_b32_e32 v160, 16, v177
	v_and_b32_e32 v161, 0xffff0000, v177
	v_pk_mul_f32 v[162:163], v[162:163], v[164:165]
	v_pk_mul_f32 v[158:159], v[158:159], v[160:161]
	v_pk_mul_f32 v[32:33], v[32:33], v[162:163]
	v_pk_mul_f32 v[28:29], v[28:29], v[158:159]
	s_waitcnt vmcnt(4)
	v_lshlrev_b32_e32 v136, 16, v186
	v_and_b32_e32 v137, 0xffff0000, v186
	v_rcp_f32_e32 v136, v136
	v_rcp_f32_e32 v137, v137
	v_lshlrev_b32_e32 v166, 16, v187
	v_and_b32_e32 v167, 0xffff0000, v187
	v_lshlrev_b32_e32 v162, 16, v188
	v_and_b32_e32 v163, 0xffff0000, v188
	v_rcp_f32_e32 v162, v162
	v_rcp_f32_e32 v163, v163
	v_lshlrev_b32_e32 v168, 16, v189
	v_and_b32_e32 v169, 0xffff0000, v189
	v_lshlrev_b32_e32 v164, 16, v182
	v_and_b32_e32 v165, 0xffff0000, v182
	v_pk_mul_f32 v[136:137], v[136:137], v[164:165]
	v_rcp_f32_e32 v158, v168
	v_pk_mul_f32 v[22:23], v[22:23], v[136:137]
	v_lshlrev_b32_e32 v136, 16, v184
	v_and_b32_e32 v137, 0xffff0000, v184
	v_pk_mul_f32 v[136:137], v[162:163], v[136:137]
	v_lshlrev_b32_e32 v162, 16, v183
	v_pk_mul_f32 v[18:19], v[18:19], v[136:137]
	v_rcp_f32_e32 v136, v166
	v_rcp_f32_e32 v137, v167
	v_and_b32_e32 v163, 0xffff0000, v183
	v_rcp_f32_e32 v159, v169
	v_pk_mul_f32 v[136:137], v[136:137], v[162:163]
	s_nop 0
	v_pk_mul_f32 v[24:25], v[24:25], v[136:137]
	v_lshlrev_b32_e32 v136, 16, v185
	v_and_b32_e32 v137, 0xffff0000, v185
	v_pk_mul_f32 v[136:137], v[158:159], v[136:137]
	s_nop 0
	v_pk_mul_f32 v[20:21], v[20:21], v[136:137]
	s_waitcnt vmcnt(2)
	s_nop 0
	v_and_b32_e32 v163, 0xffff0000, v190
	v_lshlrev_b32_e32 v157, 16, v194
	v_and_b32_e32 v162, 0xffff0000, v194
	v_lshlrev_b32_e32 v164, 16, v195
	v_and_b32_e32 v165, 0xffff0000, v195
	v_lshlrev_b32_e32 v159, 16, v196
	v_and_b32_e32 v166, 0xffff0000, v196
	v_rcp_f32_e32 v158, v157
	v_rcp_f32_e32 v160, v159
	v_rcp_f32_e32 v159, v162
	v_lshlrev_b32_e32 v167, 16, v197
	v_and_b32_e32 v168, 0xffff0000, v197
	v_rcp_f32_e32 v161, v166
	v_lshlrev_b32_e32 v162, 16, v190
	v_pk_mul_f32 v[158:159], v[158:159], v[162:163]
	v_rcp_f32_e32 v134, v167
	v_pk_mul_f32 v[14:15], v[14:15], v[158:159]
	v_lshlrev_b32_e32 v158, 16, v192
	v_and_b32_e32 v159, 0xffff0000, v192
	v_pk_mul_f32 v[158:159], v[160:161], v[158:159]
	v_lshlrev_b32_e32 v160, 16, v191
	v_and_b32_e32 v161, 0xffff0000, v191
	v_rcp_f32_e32 v135, v168
	v_lshlrev_b32_e32 v136, 16, v193
	v_and_b32_e32 v137, 0xffff0000, v193
	v_pk_mul_f32 v[10:11], v[10:11], v[158:159]
	v_pk_mul_f32 v[134:135], v[134:135], v[136:137]
	v_rcp_f32_e32 v158, v164
	v_pk_mul_f32 v[12:13], v[12:13], v[134:135]
	s_waitcnt vmcnt(0)
	s_nop 0
	v_rcp_f32_e32 v159, v165
	v_lshlrev_b32_e32 v157, 16, v202
	v_pk_mul_f32 v[158:159], v[158:159], v[160:161]
	v_lshlrev_b32_e32 v160, 16, v203
	v_pk_mul_f32 v[16:17], v[16:17], v[158:159]
	v_and_b32_e32 v158, 0xffff0000, v202
	v_and_b32_e32 v161, 0xffff0000, v203
	v_lshlrev_b32_e32 v135, 16, v204
	v_and_b32_e32 v162, 0xffff0000, v204
	v_rcp_f32_e32 v134, v157
	v_rcp_f32_e32 v136, v135
	v_rcp_f32_e32 v135, v158
	v_lshlrev_b32_e32 v163, 16, v205
	v_and_b32_e32 v164, 0xffff0000, v205
	v_rcp_f32_e32 v137, v162
	v_lshlrev_b32_e32 v158, 16, v198
	v_and_b32_e32 v159, 0xffff0000, v198
	v_pk_mul_f32 v[134:135], v[134:135], v[158:159]
	v_rcp_f32_e32 v130, v163
	v_pk_mul_f32 v[6:7], v[6:7], v[134:135]
	v_lshlrev_b32_e32 v134, 16, v200
	v_and_b32_e32 v135, 0xffff0000, v200
	v_pk_mul_f32 v[134:135], v[136:137], v[134:135]
	v_lshlrev_b32_e32 v136, 16, v199
	v_pk_mul_f32 v[2:3], v[2:3], v[134:135]
	v_rcp_f32_e32 v134, v160
	v_rcp_f32_e32 v135, v161
	v_and_b32_e32 v137, 0xffff0000, v199
	v_rcp_f32_e32 v131, v164
	v_lshlrev_b32_e32 v132, 16, v201
	v_and_b32_e32 v133, 0xffff0000, v201
	v_pk_mul_f32 v[134:135], v[134:135], v[136:137]
	v_pk_mul_f32 v[130:131], v[130:131], v[132:133]
	v_pk_mul_f32 v[8:9], v[8:9], v[134:135]
	v_pk_mul_f32 v[4:5], v[4:5], v[130:131]
	s_branch .LBB0_255
